# baseline (speedup 1.0000x reference)
.LBB0_379:
	v_mov_b32_e32 v215, v184
	v_mov_b32_e32 v5, v2
	v_lshlrev_b32_e32 v3, 3, v215
	v_ashrrev_i32_e32 v0, 4, v215
	v_and_b32_e32 v1, 0x78, v3
	v_lshlrev_b32_e32 v4, 1, v1
	v_add_u32_e32 v6, 32, v0
	v_ashrrev_i32_e32 v1, 31, v0
	v_lshlrev_b64 v[12:13], 13, v[0:1]
	v_ashrrev_i32_e32 v7, 31, v6
	v_ashrrev_i32_e32 v8, 3, v215
	v_lshl_add_u64 v[14:15], s[38:39], 0, v[12:13]
	v_lshlrev_b64 v[16:17], 13, v[6:7]
	s_xor_b64 s[78:79], s[6:7], -1
	v_lshl_add_u64 v[14:15], v[14:15], 0, v[4:5]
	v_lshl_add_u64 v[16:17], s[38:39], 0, v[16:17]
	v_ashrrev_i32_e32 v9, 31, v8
	s_and_b64 s[0:1], s[6:7], exec
	v_readfirstlane_b32 s6, v215
	v_lshlrev_b32_e32 v20, 4, v215
	v_lshl_add_u64 v[16:17], v[16:17], 0, v[4:5]
	global_load_dwordx4 v[114:117], v[14:15], off
	global_load_dwordx4 v[118:121], v[14:15], off offset:256
	global_load_dwordx4 v[122:125], v[16:17], off
	global_load_dwordx4 v[134:137], v[16:17], off offset:256
	v_lshlrev_b64 v[14:15], 7, v[8:9]
	s_cselect_b32 s5, s88, s87
	s_ashr_i32 s0, s6, 1
	v_and_b32_e32 v10, 0x70, v20
	v_lshl_add_u64 v[16:17], s[72:73], 0, v[14:15]
	v_mov_b32_e32 v11, v2
	s_andn2_b32 s0, s0, 31
	v_lshl_add_u64 v[16:17], v[16:17], 0, v[10:11]
	v_and_b32_e32 v217, 31, v215
	s_add_i32 s80, s0, s5
	global_load_dwordx4 v[178:181], v[16:17], off
	v_bfe_u32 v216, v215, 5, 1
	v_or_b32_e32 v5, s80, v217
	v_and_b32_e32 v239, 15, v215
	v_or_b32_e32 v239, s80, v239
	v_mov_b64_e32 v[16:17], s[2:3]
	s_movk_i32 s0, 0x1800
	v_mad_i64_i32 v[16:17], s[0:1], v239, s0, v[16:17]
	v_lshlrev_b32_e32 v18, 4, v216
	v_mov_b32_e32 v19, v2
	v_bfe_u32 v236, v215, 4, 2
	v_lshlrev_b32_e32 v236, 4, v236
	v_mov_b32_e32 v237, v2
	v_lshl_add_u64 v[16:17], v[16:17], 0, v[236:237]
	global_load_dwordx4 v[126:129], v[16:17], off
	global_load_dwordx4 v[130:133], v[16:17], off offset:64
	global_load_dwordx4 v[138:141], v[16:17], off offset:128
	global_load_dwordx4 v[142:145], v[16:17], off offset:192
	global_load_dwordx4 v[146:149], v[16:17], off offset:256
	global_load_dwordx4 v[150:153], v[16:17], off offset:320
	v_mov_b32_e32 v236, 0x18000
	v_lshl_add_u64 v[16:17], v[16:17], 0, v[236:237]
	global_load_dwordx4 v[154:157], v[16:17], off
	global_load_dwordx4 v[158:161], v[16:17], off offset:64
	global_load_dwordx4 v[162:165], v[16:17], off offset:128
	global_load_dwordx4 v[166:169], v[16:17], off offset:192
	global_load_dwordx4 v[170:173], v[16:17], off offset:256
	global_load_dwordx4 v[174:177], v[16:17], off offset:320
	v_lshlrev_b32_e32 v213, 2, v216
	v_sub_u32_e32 v218, v5, v213
	v_and_b32_e32 v5, 0xfffff0, v0
	v_lshlrev_b32_e32 v7, 1, v0
	v_and_or_b32 v5, v7, 8, v5
	v_lshrrev_b32_e32 v7, 1, v0
	v_lshrrev_b32_e32 v5, 1, v5
	v_bfe_u32 v9, v3, 5, 2
	v_and_b32_e32 v11, 3, v0
	v_or_b32_e32 v5, v5, v9
	v_and_or_b32 v7, v7, 4, v11
	v_lshlrev_b32_e32 v5, 9, v5
	v_lshlrev_b32_e32 v7, 6, v7
	v_and_b32_e32 v11, 48, v4
	v_or3_b32 v219, v5, v7, v11
	v_and_b32_e32 v5, 0xfffff0, v6
	v_lshlrev_b32_e32 v6, 1, v6
	v_and_or_b32 v5, v6, 8, v5
	v_lshrrev_b32_e32 v5, 1, v5
	v_or_b32_e32 v5, v5, v9
	v_lshlrev_b32_e32 v5, 9, v5
	v_or3_b32 v220, v5, v7, v11
	v_lshlrev_b32_e32 v0, 8, v0
	v_and_b32_e32 v5, 0xf0, v215
	v_and_b32_e32 v1, 63, v215
	v_bitop3_b32 v221, v4, v0, v5 bitop3:0xde
	v_lshlrev_b32_e32 v0, 7, v8
	v_and_b32_e32 v4, 0x70, v215
	v_bitop3_b32 v222, v10, v0, v4 bitop3:0xde
	v_lshlrev_b32_e32 v0, 3, v1
	v_and_b32_e32 v4, 0xc0, v20
	v_lshlrev_b32_e32 v5, 1, v215
	v_and_or_b32 v4, v0, 24, v4
	v_and_b32_e32 v5, 32, v5
	v_and_b32_e32 v0, 0x100, v0
	s_movk_i32 s1, 0xf0
	v_or3_b32 v223, v4, v5, v0
	v_and_b32_e32 v0, 0xf0, v20
	v_bitop3_b32 v20, v18, v20, s1 bitop3:0x78
	s_movk_i32 s1, 0x80
	v_bitop3_b32 v24, v18, v0, s1 bitop3:0x36
	s_movk_i32 s1, 0xa0
	s_addk_i32 s5, 0x100
	v_bitop3_b32 v25, v18, v0, s1 bitop3:0x36
	s_movk_i32 s1, 0xc0
	s_lshr_b32 s90, s5, 6
	s_movk_i32 s5, 0x60
	v_bitop3_b32 v26, v18, v0, s1 bitop3:0x36
	s_movk_i32 s1, 0xe0
	s_and_b32 s0, s6, 0x3fffffc0
	v_bitop3_b32 v21, v18, v0, 32 bitop3:0x36
	v_bitop3_b32 v22, v18, v0, 64 bitop3:0x36
	v_bitop3_b32 v23, v18, v0, s5 bitop3:0x36
	v_bitop3_b32 v27, v18, v0, s1 bitop3:0x36
	v_lshlrev_b32_e32 v0, 7, v217
	s_movk_i32 s1, 0x70
	s_lshl_b32 s0, s0, 2
	v_or_b32_e32 v225, 0x10000, v0
	v_and_b32_e32 v4, 0x70, v3
	v_bitop3_b32 v227, v18, v3, s1 bitop3:0x78
	v_or_b32_e32 v231, 0x12000, v0
	v_and_b32_e32 v0, 7, v215
	v_and_b32_e32 v3, 15, v215
	s_add_i32 s0, s0, 0x14000
	v_lshlrev_b32_e32 v19, 8, v217
	v_lshl_or_b32 v14, v0, 4, v14
	v_lshl_or_b32 v12, v3, 4, v12
	v_mov_b32_e32 v16, v2
	v_mov_b32_e32 v17, v2
	v_bitop3_b32 v228, v18, v4, 32 bitop3:0x36
	v_bitop3_b32 v229, v18, v4, 64 bitop3:0x36
	v_bitop3_b32 v230, v18, v4, s5 bitop3:0x36
	v_cmp_gt_u32_e64 s[6:7], 32, v1
	v_or_b32_e32 v214, s0, v18
	v_lshl_add_u64 v[0:1], s[74:75], 0, v[14:15]
	v_lshl_add_u64 v[182:183], s[76:77], 0, v[12:13]
	v_mov_b32_e32 v3, v2
	v_mov_b32_e32 v4, v2
	v_mov_b32_e32 v5, v2
	v_mov_b32_e32 v6, v2
	v_mov_b32_e32 v7, v2
	v_mov_b32_e32 v8, v2
	v_mov_b32_e32 v9, v2
	v_mov_b32_e32 v10, v2
	v_mov_b32_e32 v11, v2
	v_mov_b32_e32 v12, v2
	v_mov_b32_e32 v13, v2
	v_mov_b32_e32 v14, v2
	v_mov_b32_e32 v15, v2
	v_add_u32_e32 v233, v19, v20
	v_add_u32_e32 v234, v19, v21
	v_add_u32_e32 v235, v19, v22
	v_add_u32_e32 v236, v19, v23
	v_add_u32_e32 v237, v19, v24
	v_add_u32_e32 v238, v19, v25
	v_add_u32_e32 v239, v19, v26
	v_add_u32_e32 v240, v19, v27
	v_mov_b64_e32 v[32:33], v[16:17]
	v_mov_b64_e32 v[48:49], v[16:17]
	v_mov_b64_e32 v[64:65], v[16:17]
	v_mov_b64_e32 v[80:81], v[16:17]
	s_mov_b32 s81, 63
	s_mov_b32 s89, 2
	v_add_u32_e32 v224, 0x10000, v222
	s_or_b32 s91, s80, 31
	v_lshl_or_b32 v226, v217, 2, s0
	v_mov_b32_e32 v241, 0
	v_mov_b32_e32 v232, 0xf149f2ca
	v_mov_b64_e32 v[30:31], v[14:15]
	v_mov_b64_e32 v[28:29], v[12:13]
	v_mov_b64_e32 v[26:27], v[10:11]
	v_mov_b64_e32 v[24:25], v[8:9]
	v_mov_b64_e32 v[22:23], v[6:7]
	v_mov_b64_e32 v[20:21], v[4:5]
	v_mov_b64_e32 v[18:19], v[2:3]
	v_mov_b64_e32 v[46:47], v[14:15]
	v_mov_b64_e32 v[44:45], v[12:13]
	v_mov_b64_e32 v[42:43], v[10:11]
	v_mov_b64_e32 v[40:41], v[8:9]
	v_mov_b64_e32 v[38:39], v[6:7]
	v_mov_b64_e32 v[36:37], v[4:5]
	v_mov_b64_e32 v[34:35], v[2:3]
	v_mov_b64_e32 v[62:63], v[14:15]
	v_mov_b64_e32 v[60:61], v[12:13]
	v_mov_b64_e32 v[58:59], v[10:11]
	v_mov_b64_e32 v[56:57], v[8:9]
	v_mov_b64_e32 v[54:55], v[6:7]
	v_mov_b64_e32 v[52:53], v[4:5]
	v_mov_b64_e32 v[50:51], v[2:3]
	v_mov_b64_e32 v[78:79], v[14:15]
	v_mov_b64_e32 v[76:77], v[12:13]
	v_mov_b64_e32 v[74:75], v[10:11]
	v_mov_b64_e32 v[72:73], v[8:9]
	v_mov_b64_e32 v[70:71], v[6:7]
	v_mov_b64_e32 v[68:69], v[4:5]
	v_mov_b64_e32 v[66:67], v[2:3]
	v_and_b32_e32 v239, 15, v215
	v_bfe_u32 v240, v215, 4, 2
	v_and_b32_e32 v233, 3, v239
	v_and_b32_e32 v234, 4, v239
	v_lshl_or_b32 v233, v234, 1, v233
	v_and_b32_e32 v234, 8, v239
	v_lshrrev_b32_e32 v234, 1, v234
	v_or_b32_e32 v239, v233, v234
	v_xor_b32_e32 v233, v240, v239
	v_lshlrev_b32_e32 v233, 4, v233
	v_lshl_or_b32 v233, v239, 8, v233
	v_xor_b32_e32 v234, 64, v233
	v_xor_b32_e32 v235, 0x80, v233
	v_xor_b32_e32 v236, 0xc0, v233
	v_lshrrev_b32_e32 v237, 1, v239
	v_xor_b32_e32 v237, v240, v237
	v_lshlrev_b32_e32 v237, 4, v237
	v_lshl_or_b32 v237, v239, 7, v237
	v_or_b32_e32 v237, 0x10000, v237
	v_xor_b32_e32 v238, 64, v237
	s_waitcnt vmcnt(0)
	ds_write_b128 v221, v[114:117] offset:32768
	s_waitcnt vmcnt(0)
	ds_write_b128 v221, v[122:125] offset:40960
	ds_write_b128 v219, v[118:121]
	s_waitcnt vmcnt(0)
	ds_write_b128 v220, v[134:137]
	s_waitcnt vmcnt(0)
	ds_write_b128 v224, v[178:181]
	s_waitcnt lgkmcnt(0)
	s_barrier
	s_branch .LBB0_381

.LBB0_389:
	v_mov_b32_e32 v82, 0
	ds_read_b128 v[4:7], v233 offset:32768
	ds_read_b128 v[8:11], v233 offset:36864
	ds_read_b128 v[12:15], v233 offset:40960
	v_mov_b32_e32 v83, v82
	v_mov_b32_e32 v84, v82
	v_mov_b32_e32 v85, v82
	v_mov_b32_e32 v86, v82
	v_mov_b32_e32 v87, v82
	v_mov_b32_e32 v88, v82
	v_mov_b32_e32 v89, v82
	v_mov_b32_e32 v90, v82
	v_mov_b32_e32 v91, v82
	v_mov_b32_e32 v92, v82
	v_mov_b32_e32 v93, v82
	v_mov_b32_e32 v94, v82
	v_mov_b32_e32 v95, v82
	v_mov_b32_e32 v96, v82
	v_mov_b32_e32 v97, v82
	v_mov_b32_e32 v98, v82
	v_mov_b32_e32 v99, v82
	v_mov_b32_e32 v100, v82
	v_mov_b32_e32 v101, v82
	v_mov_b32_e32 v102, v82
	v_mov_b32_e32 v103, v82
	v_mov_b32_e32 v104, v82
	v_mov_b32_e32 v105, v82
	v_mov_b32_e32 v106, v82
	v_mov_b32_e32 v107, v82
	v_mov_b32_e32 v108, v82
	v_mov_b32_e32 v109, v82
	v_mov_b32_e32 v110, v82
	v_mov_b32_e32 v111, v82
	v_mov_b32_e32 v112, v82
	v_mov_b32_e32 v113, v82
	s_cmp_le_i32 s81, s80
	s_nop 1
	s_waitcnt lgkmcnt(2)
	v_mfma_f32_16x16x32_bf16 v[98:101], v[4:7], v[126:129], v[98:101]
	v_mfma_f32_16x16x32_bf16 v[102:105], v[4:7], v[154:157], v[102:105]
	ds_read_b128 v[4:7], v233 offset:45056
	s_waitcnt lgkmcnt(2)
	v_mfma_f32_16x16x32_bf16 v[106:109], v[8:11], v[126:129], v[106:109]
	v_mfma_f32_16x16x32_bf16 v[110:113], v[8:11], v[154:157], v[110:113]
	ds_read_b128 v[8:11], v234 offset:32768
	s_waitcnt lgkmcnt(2)
	v_mfma_f32_16x16x32_bf16 v[82:85], v[12:15], v[126:129], v[82:85]
	v_mfma_f32_16x16x32_bf16 v[86:89], v[12:15], v[154:157], v[86:89]
	ds_read_b128 v[12:15], v234 offset:36864
	s_waitcnt lgkmcnt(2)
	v_mfma_f32_16x16x32_bf16 v[90:93], v[4:7], v[126:129], v[90:93]
	v_mfma_f32_16x16x32_bf16 v[94:97], v[4:7], v[154:157], v[94:97]
	ds_read_b128 v[4:7], v234 offset:40960
	s_waitcnt lgkmcnt(2)
	v_mfma_f32_16x16x32_bf16 v[98:101], v[8:11], v[130:133], v[98:101]
	v_mfma_f32_16x16x32_bf16 v[102:105], v[8:11], v[158:161], v[102:105]
	ds_read_b128 v[8:11], v234 offset:45056
	s_waitcnt lgkmcnt(2)
	v_mfma_f32_16x16x32_bf16 v[106:109], v[12:15], v[130:133], v[106:109]
	v_mfma_f32_16x16x32_bf16 v[110:113], v[12:15], v[158:161], v[110:113]
	ds_read_b128 v[12:15], v235 offset:32768
	s_waitcnt lgkmcnt(2)
	v_mfma_f32_16x16x32_bf16 v[82:85], v[4:7], v[130:133], v[82:85]
	v_mfma_f32_16x16x32_bf16 v[86:89], v[4:7], v[158:161], v[86:89]
	ds_read_b128 v[4:7], v235 offset:36864
	s_waitcnt lgkmcnt(2)
	v_mfma_f32_16x16x32_bf16 v[90:93], v[8:11], v[130:133], v[90:93]
	v_mfma_f32_16x16x32_bf16 v[94:97], v[8:11], v[158:161], v[94:97]
	ds_read_b128 v[8:11], v235 offset:40960
	s_waitcnt lgkmcnt(2)
	v_mfma_f32_16x16x32_bf16 v[98:101], v[12:15], v[138:141], v[98:101]
	v_mfma_f32_16x16x32_bf16 v[102:105], v[12:15], v[162:165], v[102:105]
	ds_read_b128 v[12:15], v235 offset:45056
	s_waitcnt lgkmcnt(2)
	v_mfma_f32_16x16x32_bf16 v[106:109], v[4:7], v[138:141], v[106:109]
	v_mfma_f32_16x16x32_bf16 v[110:113], v[4:7], v[162:165], v[110:113]
	ds_read_b128 v[4:7], v236 offset:32768
	s_waitcnt lgkmcnt(2)
	v_mfma_f32_16x16x32_bf16 v[82:85], v[8:11], v[138:141], v[82:85]
	v_mfma_f32_16x16x32_bf16 v[86:89], v[8:11], v[162:165], v[86:89]
	ds_read_b128 v[8:11], v236 offset:36864
	s_waitcnt lgkmcnt(2)
	v_mfma_f32_16x16x32_bf16 v[90:93], v[12:15], v[138:141], v[90:93]
	v_mfma_f32_16x16x32_bf16 v[94:97], v[12:15], v[162:165], v[94:97]
	ds_read_b128 v[12:15], v236 offset:40960
	s_waitcnt lgkmcnt(2)
	v_mfma_f32_16x16x32_bf16 v[98:101], v[4:7], v[142:145], v[98:101]
	v_mfma_f32_16x16x32_bf16 v[102:105], v[4:7], v[166:169], v[102:105]
	ds_read_b128 v[4:7], v236 offset:45056
	s_waitcnt lgkmcnt(2)
	v_mfma_f32_16x16x32_bf16 v[106:109], v[8:11], v[142:145], v[106:109]
	v_mfma_f32_16x16x32_bf16 v[110:113], v[8:11], v[166:169], v[110:113]
	ds_read_b128 v[8:11], v237
	s_waitcnt lgkmcnt(2)
	v_mfma_f32_16x16x32_bf16 v[82:85], v[12:15], v[142:145], v[82:85]
	v_mfma_f32_16x16x32_bf16 v[86:89], v[12:15], v[166:169], v[86:89]
	ds_read_b128 v[12:15], v237 offset:2048
	s_waitcnt lgkmcnt(2)
	v_mfma_f32_16x16x32_bf16 v[90:93], v[4:7], v[142:145], v[90:93]
	v_mfma_f32_16x16x32_bf16 v[94:97], v[4:7], v[166:169], v[94:97]
	ds_read_b128 v[4:7], v237 offset:4096
	s_waitcnt lgkmcnt(2)
	v_mfma_f32_16x16x32_bf16 v[98:101], v[8:11], v[146:149], v[98:101]
	v_mfma_f32_16x16x32_bf16 v[102:105], v[8:11], v[170:173], v[102:105]
	ds_read_b128 v[8:11], v237 offset:6144
	s_waitcnt lgkmcnt(2)
	v_mfma_f32_16x16x32_bf16 v[106:109], v[12:15], v[146:149], v[106:109]
	v_mfma_f32_16x16x32_bf16 v[110:113], v[12:15], v[170:173], v[110:113]
	ds_read_b128 v[12:15], v238
	s_waitcnt lgkmcnt(2)
	v_mfma_f32_16x16x32_bf16 v[82:85], v[4:7], v[146:149], v[82:85]
	v_mfma_f32_16x16x32_bf16 v[86:89], v[4:7], v[170:173], v[86:89]
	ds_read_b128 v[4:7], v238 offset:2048
	s_waitcnt lgkmcnt(2)
	v_mfma_f32_16x16x32_bf16 v[90:93], v[8:11], v[146:149], v[90:93]
	v_mfma_f32_16x16x32_bf16 v[94:97], v[8:11], v[170:173], v[94:97]
	ds_read_b128 v[8:11], v238 offset:4096
	s_waitcnt lgkmcnt(2)
	v_mfma_f32_16x16x32_bf16 v[98:101], v[12:15], v[150:153], v[98:101]
	v_mfma_f32_16x16x32_bf16 v[102:105], v[12:15], v[174:177], v[102:105]
	ds_read_b128 v[12:15], v238 offset:6144
	s_waitcnt lgkmcnt(2)
	v_mfma_f32_16x16x32_bf16 v[106:109], v[4:7], v[150:153], v[106:109]
	v_mfma_f32_16x16x32_bf16 v[110:113], v[4:7], v[174:177], v[110:113]
	s_waitcnt lgkmcnt(1)
	v_mfma_f32_16x16x32_bf16 v[82:85], v[8:11], v[150:153], v[82:85]
	v_mfma_f32_16x16x32_bf16 v[86:89], v[8:11], v[174:177], v[86:89]
	s_waitcnt lgkmcnt(0)
	v_mfma_f32_16x16x32_bf16 v[90:93], v[12:15], v[150:153], v[90:93]
	v_mfma_f32_16x16x32_bf16 v[94:97], v[12:15], v[174:177], v[94:97]
	s_nop 7
	s_nop 3
	v_permlane16_swap_b32_e32 v98, v102
	v_permlane16_swap_b32_e32 v99, v103
	v_permlane16_swap_b32_e32 v100, v104
	v_permlane16_swap_b32_e32 v101, v105
	v_permlane16_swap_b32_e32 v106, v110
	v_permlane16_swap_b32_e32 v107, v111
	v_permlane16_swap_b32_e32 v108, v112
	v_permlane16_swap_b32_e32 v109, v113
	v_permlane16_swap_b32_e32 v82, v86
	v_permlane16_swap_b32_e32 v83, v87
	v_permlane16_swap_b32_e32 v84, v88
	v_permlane16_swap_b32_e32 v85, v89
	v_permlane16_swap_b32_e32 v90, v94
	v_permlane16_swap_b32_e32 v91, v95
	v_permlane16_swap_b32_e32 v92, v96
	v_permlane16_swap_b32_e32 v93, v97
	s_cbranch_scc1 .LBB0_391
	v_cmp_gt_i32_e64 s[68:69], 26, v218
	v_cmp_gt_i32_e64 s[70:71], 27, v218
	v_cmp_gt_i32_e64 s[66:67], 25, v218
	s_and_b64 s[68:69], s[70:71], s[68:69]
	v_cmp_gt_i32_e64 s[64:65], 24, v218
	s_and_b64 s[66:67], s[68:69], s[66:67]
	v_cmp_gt_i32_e64 s[62:63], 19, v218
	s_and_b64 s[64:65], s[66:67], s[64:65]
	v_cmp_gt_i32_e64 s[60:61], 18, v218
	s_and_b64 s[62:63], s[64:65], s[62:63]
	v_cmp_gt_i32_e64 s[58:59], 17, v218
	s_and_b64 s[60:61], s[62:63], s[60:61]
	v_cmp_gt_i32_e64 s[56:57], 16, v218
	s_and_b64 s[58:59], s[60:61], s[58:59]
	v_cmp_gt_i32_e64 s[54:55], 11, v218
	s_and_b64 s[56:57], s[58:59], s[56:57]
	v_cmp_gt_i32_e64 s[52:53], 10, v218
	s_and_b64 s[54:55], s[56:57], s[54:55]
	v_cmp_gt_i32_e64 s[50:51], 9, v218
	s_and_b64 s[52:53], s[54:55], s[52:53]
	v_cmp_gt_i32_e64 s[48:49], 8, v218
	s_and_b64 s[50:51], s[52:53], s[50:51]
	v_cmp_gt_i32_e64 s[46:47], 3, v218
	s_and_b64 s[48:49], s[50:51], s[48:49]
	v_cmp_gt_i32_e64 s[44:45], 2, v218
	s_and_b64 s[46:47], s[48:49], s[46:47]
	v_cmp_gt_i32_e64 s[42:43], 1, v218
	s_and_b64 s[44:45], s[46:47], s[44:45]
	v_cmp_gt_i32_e64 s[40:41], 0, v218
	s_and_b64 s[42:43], s[44:45], s[42:43]
	s_and_b64 s[40:41], s[42:43], s[40:41]
	v_cmp_gt_i32_e64 s[36:37], 58, v218
	v_cndmask_b32_e64 v98, v98, v210, s[40:41]
	v_cmp_gt_i32_e64 s[40:41], 59, v218
	v_cmp_gt_i32_e64 s[34:35], 57, v218
	s_and_b64 s[36:37], s[40:41], s[36:37]
	v_cmp_gt_i32_e64 s[30:31], 56, v218
	s_and_b64 s[34:35], s[36:37], s[34:35]
	v_cmp_gt_i32_e64 s[28:29], 51, v218
	s_and_b64 s[30:31], s[34:35], s[30:31]
	v_cmp_gt_i32_e64 s[26:27], 50, v218
	s_and_b64 s[28:29], s[30:31], s[28:29]
	v_cmp_gt_i32_e64 s[24:25], 49, v218
	s_and_b64 s[26:27], s[28:29], s[26:27]
	v_cmp_gt_i32_e64 s[22:23], 48, v218
	s_and_b64 s[24:25], s[26:27], s[24:25]
	v_cmp_gt_i32_e64 s[20:21], 43, v218
	s_and_b64 s[22:23], s[24:25], s[22:23]
	v_cmp_gt_i32_e64 s[18:19], 42, v218
	s_and_b64 s[20:21], s[22:23], s[20:21]
	v_cmp_gt_i32_e64 s[16:17], 41, v218
	s_and_b64 s[18:19], s[20:21], s[18:19]
	v_cmp_gt_i32_e64 s[14:15], 40, v218
	s_and_b64 s[16:17], s[18:19], s[16:17]
	v_cmp_gt_i32_e64 s[12:13], 35, v218
	s_and_b64 s[14:15], s[16:17], s[14:15]
	v_cmp_gt_i32_e64 s[10:11], 34, v218
	s_and_b64 s[12:13], s[14:15], s[12:13]
	v_cmp_gt_i32_e64 s[8:9], 33, v218
	s_and_b64 s[10:11], s[12:13], s[10:11]
	v_cmp_gt_i32_e32 vcc, 32, v218
	s_and_b64 s[8:9], s[10:11], s[8:9]
	s_and_b64 vcc, s[8:9], vcc
	v_cndmask_b32_e64 v113, v113, v210, s[70:71]
	v_cndmask_b32_e64 v112, v112, v210, s[68:69]
	v_cndmask_b32_e64 v111, v111, v210, s[66:67]
	v_cndmask_b32_e64 v110, v110, v210, s[64:65]
	v_cndmask_b32_e64 v109, v109, v210, s[62:63]
	v_cndmask_b32_e64 v108, v108, v210, s[60:61]
	v_cndmask_b32_e64 v107, v107, v210, s[58:59]
	v_cndmask_b32_e64 v106, v106, v210, s[56:57]
	v_cndmask_b32_e64 v105, v105, v210, s[54:55]
	v_cndmask_b32_e64 v104, v104, v210, s[52:53]
	v_cndmask_b32_e64 v103, v103, v210, s[50:51]
	v_cndmask_b32_e64 v102, v102, v210, s[48:49]
	v_cndmask_b32_e64 v101, v101, v210, s[46:47]
	v_cndmask_b32_e64 v100, v100, v210, s[44:45]
	v_cndmask_b32_e64 v99, v99, v210, s[42:43]
	v_cndmask_b32_e64 v97, v97, v210, s[40:41]
	v_cndmask_b32_e64 v96, v96, v210, s[36:37]
	v_cndmask_b32_e64 v95, v95, v210, s[34:35]
	v_cndmask_b32_e64 v94, v94, v210, s[30:31]
	v_cndmask_b32_e64 v93, v93, v210, s[28:29]
	v_cndmask_b32_e64 v92, v92, v210, s[26:27]
	v_cndmask_b32_e64 v91, v91, v210, s[24:25]
	v_cndmask_b32_e64 v90, v90, v210, s[22:23]
	v_cndmask_b32_e64 v89, v89, v210, s[20:21]
	v_cndmask_b32_e64 v88, v88, v210, s[18:19]
	v_cndmask_b32_e64 v87, v87, v210, s[16:17]
	v_cndmask_b32_e64 v86, v86, v210, s[14:15]
	v_cndmask_b32_e64 v85, v85, v210, s[12:13]
	v_cndmask_b32_e64 v84, v84, v210, s[10:11]
	v_cndmask_b32_e64 v83, v83, v210, s[8:9]
	v_cndmask_b32_e32 v82, v82, v210, vcc

.LBB0_397:
	v_mov_b32_e32 v82, 0
	ds_read_b128 v[4:7], v233 offset:49152
	ds_read_b128 v[8:11], v233 offset:53248
	ds_read_b128 v[12:15], v233 offset:57344
	v_mov_b32_e32 v83, v82
	v_mov_b32_e32 v84, v82
	v_mov_b32_e32 v85, v82
	v_mov_b32_e32 v86, v82
	v_mov_b32_e32 v87, v82
	v_mov_b32_e32 v88, v82
	v_mov_b32_e32 v89, v82
	v_mov_b32_e32 v90, v82
	v_mov_b32_e32 v91, v82
	v_mov_b32_e32 v92, v82
	v_mov_b32_e32 v93, v82
	v_mov_b32_e32 v94, v82
	v_mov_b32_e32 v95, v82
	v_mov_b32_e32 v96, v82
	v_mov_b32_e32 v97, v82
	v_mov_b32_e32 v98, v82
	v_mov_b32_e32 v99, v82
	v_mov_b32_e32 v100, v82
	v_mov_b32_e32 v101, v82
	v_mov_b32_e32 v102, v82
	v_mov_b32_e32 v103, v82
	v_mov_b32_e32 v104, v82
	v_mov_b32_e32 v105, v82
	v_mov_b32_e32 v106, v82
	v_mov_b32_e32 v107, v82
	v_mov_b32_e32 v108, v82
	v_mov_b32_e32 v109, v82
	v_mov_b32_e32 v110, v82
	v_mov_b32_e32 v111, v82
	v_mov_b32_e32 v112, v82
	v_mov_b32_e32 v113, v82
	s_add_i32 s0, s81, 64
	s_cmp_le_i32 s0, s80
	s_nop 1
	s_waitcnt lgkmcnt(2)
	v_mfma_f32_16x16x32_bf16 v[98:101], v[4:7], v[126:129], v[98:101]
	v_mfma_f32_16x16x32_bf16 v[102:105], v[4:7], v[154:157], v[102:105]
	ds_read_b128 v[4:7], v233 offset:61440
	s_waitcnt lgkmcnt(2)
	v_mfma_f32_16x16x32_bf16 v[106:109], v[8:11], v[126:129], v[106:109]
	v_mfma_f32_16x16x32_bf16 v[110:113], v[8:11], v[154:157], v[110:113]
	ds_read_b128 v[8:11], v234 offset:49152
	s_waitcnt lgkmcnt(2)
	v_mfma_f32_16x16x32_bf16 v[82:85], v[12:15], v[126:129], v[82:85]
	v_mfma_f32_16x16x32_bf16 v[86:89], v[12:15], v[154:157], v[86:89]
	ds_read_b128 v[12:15], v234 offset:53248
	s_waitcnt lgkmcnt(2)
	v_mfma_f32_16x16x32_bf16 v[90:93], v[4:7], v[126:129], v[90:93]
	v_mfma_f32_16x16x32_bf16 v[94:97], v[4:7], v[154:157], v[94:97]
	ds_read_b128 v[4:7], v234 offset:57344
	s_waitcnt lgkmcnt(2)
	v_mfma_f32_16x16x32_bf16 v[98:101], v[8:11], v[130:133], v[98:101]
	v_mfma_f32_16x16x32_bf16 v[102:105], v[8:11], v[158:161], v[102:105]
	ds_read_b128 v[8:11], v234 offset:61440
	s_waitcnt lgkmcnt(2)
	v_mfma_f32_16x16x32_bf16 v[106:109], v[12:15], v[130:133], v[106:109]
	v_mfma_f32_16x16x32_bf16 v[110:113], v[12:15], v[158:161], v[110:113]
	ds_read_b128 v[12:15], v235 offset:49152
	s_waitcnt lgkmcnt(2)
	v_mfma_f32_16x16x32_bf16 v[82:85], v[4:7], v[130:133], v[82:85]
	v_mfma_f32_16x16x32_bf16 v[86:89], v[4:7], v[158:161], v[86:89]
	ds_read_b128 v[4:7], v235 offset:53248
	s_waitcnt lgkmcnt(2)
	v_mfma_f32_16x16x32_bf16 v[90:93], v[8:11], v[130:133], v[90:93]
	v_mfma_f32_16x16x32_bf16 v[94:97], v[8:11], v[158:161], v[94:97]
	ds_read_b128 v[8:11], v235 offset:57344
	s_waitcnt lgkmcnt(2)
	v_mfma_f32_16x16x32_bf16 v[98:101], v[12:15], v[138:141], v[98:101]
	v_mfma_f32_16x16x32_bf16 v[102:105], v[12:15], v[162:165], v[102:105]
	ds_read_b128 v[12:15], v235 offset:61440
	s_waitcnt lgkmcnt(2)
	v_mfma_f32_16x16x32_bf16 v[106:109], v[4:7], v[138:141], v[106:109]
	v_mfma_f32_16x16x32_bf16 v[110:113], v[4:7], v[162:165], v[110:113]
	ds_read_b128 v[4:7], v236 offset:49152
	s_waitcnt lgkmcnt(2)
	v_mfma_f32_16x16x32_bf16 v[82:85], v[8:11], v[138:141], v[82:85]
	v_mfma_f32_16x16x32_bf16 v[86:89], v[8:11], v[162:165], v[86:89]
	ds_read_b128 v[8:11], v236 offset:53248
	s_waitcnt lgkmcnt(2)
	v_mfma_f32_16x16x32_bf16 v[90:93], v[12:15], v[138:141], v[90:93]
	v_mfma_f32_16x16x32_bf16 v[94:97], v[12:15], v[162:165], v[94:97]
	ds_read_b128 v[12:15], v236 offset:57344
	s_waitcnt lgkmcnt(2)
	v_mfma_f32_16x16x32_bf16 v[98:101], v[4:7], v[142:145], v[98:101]
	v_mfma_f32_16x16x32_bf16 v[102:105], v[4:7], v[166:169], v[102:105]
	ds_read_b128 v[4:7], v236 offset:61440
	s_waitcnt lgkmcnt(2)
	v_mfma_f32_16x16x32_bf16 v[106:109], v[8:11], v[142:145], v[106:109]
	v_mfma_f32_16x16x32_bf16 v[110:113], v[8:11], v[166:169], v[110:113]
	ds_read_b128 v[8:11], v237 offset:8192
	s_waitcnt lgkmcnt(2)
	v_mfma_f32_16x16x32_bf16 v[82:85], v[12:15], v[142:145], v[82:85]
	v_mfma_f32_16x16x32_bf16 v[86:89], v[12:15], v[166:169], v[86:89]
	ds_read_b128 v[12:15], v237 offset:10240
	s_waitcnt lgkmcnt(2)
	v_mfma_f32_16x16x32_bf16 v[90:93], v[4:7], v[142:145], v[90:93]
	v_mfma_f32_16x16x32_bf16 v[94:97], v[4:7], v[166:169], v[94:97]
	ds_read_b128 v[4:7], v237 offset:12288
	s_waitcnt lgkmcnt(2)
	v_mfma_f32_16x16x32_bf16 v[98:101], v[8:11], v[146:149], v[98:101]
	v_mfma_f32_16x16x32_bf16 v[102:105], v[8:11], v[170:173], v[102:105]
	ds_read_b128 v[8:11], v237 offset:14336
	s_waitcnt lgkmcnt(2)
	v_mfma_f32_16x16x32_bf16 v[106:109], v[12:15], v[146:149], v[106:109]
	v_mfma_f32_16x16x32_bf16 v[110:113], v[12:15], v[170:173], v[110:113]
	ds_read_b128 v[12:15], v238 offset:8192
	s_waitcnt lgkmcnt(2)
	v_mfma_f32_16x16x32_bf16 v[82:85], v[4:7], v[146:149], v[82:85]
	v_mfma_f32_16x16x32_bf16 v[86:89], v[4:7], v[170:173], v[86:89]
	ds_read_b128 v[4:7], v238 offset:10240
	s_waitcnt lgkmcnt(2)
	v_mfma_f32_16x16x32_bf16 v[90:93], v[8:11], v[146:149], v[90:93]
	v_mfma_f32_16x16x32_bf16 v[94:97], v[8:11], v[170:173], v[94:97]
	ds_read_b128 v[8:11], v238 offset:12288
	s_waitcnt lgkmcnt(2)
	v_mfma_f32_16x16x32_bf16 v[98:101], v[12:15], v[150:153], v[98:101]
	v_mfma_f32_16x16x32_bf16 v[102:105], v[12:15], v[174:177], v[102:105]
	ds_read_b128 v[12:15], v238 offset:14336
	s_waitcnt lgkmcnt(2)
	v_mfma_f32_16x16x32_bf16 v[106:109], v[4:7], v[150:153], v[106:109]
	v_mfma_f32_16x16x32_bf16 v[110:113], v[4:7], v[174:177], v[110:113]
	s_waitcnt lgkmcnt(1)
	v_mfma_f32_16x16x32_bf16 v[82:85], v[8:11], v[150:153], v[82:85]
	v_mfma_f32_16x16x32_bf16 v[86:89], v[8:11], v[174:177], v[86:89]
	s_waitcnt lgkmcnt(0)
	v_mfma_f32_16x16x32_bf16 v[90:93], v[12:15], v[150:153], v[90:93]
	v_mfma_f32_16x16x32_bf16 v[94:97], v[12:15], v[174:177], v[94:97]
	s_nop 7
	s_nop 3
	v_permlane16_swap_b32_e32 v98, v102
	v_permlane16_swap_b32_e32 v99, v103
	v_permlane16_swap_b32_e32 v100, v104
	v_permlane16_swap_b32_e32 v101, v105
	v_permlane16_swap_b32_e32 v106, v110
	v_permlane16_swap_b32_e32 v107, v111
	v_permlane16_swap_b32_e32 v108, v112
	v_permlane16_swap_b32_e32 v109, v113
	v_permlane16_swap_b32_e32 v82, v86
	v_permlane16_swap_b32_e32 v83, v87
	v_permlane16_swap_b32_e32 v84, v88
	v_permlane16_swap_b32_e32 v85, v89
	v_permlane16_swap_b32_e32 v90, v94
	v_permlane16_swap_b32_e32 v91, v95
	v_permlane16_swap_b32_e32 v92, v96
	v_permlane16_swap_b32_e32 v93, v97
	s_cbranch_scc1 .LBB0_399
	v_subrev_u32_e32 v3, 64, v218
	v_cmp_gt_i32_e64 s[68:69], 26, v3
	v_cmp_gt_i32_e64 s[70:71], 27, v3
	v_cmp_gt_i32_e64 s[66:67], 25, v3
	s_and_b64 s[68:69], s[70:71], s[68:69]
	v_cmp_gt_i32_e64 s[64:65], 24, v3
	s_and_b64 s[66:67], s[68:69], s[66:67]
	v_cmp_gt_i32_e64 s[62:63], 19, v3
	s_and_b64 s[64:65], s[66:67], s[64:65]
	v_cmp_gt_i32_e64 s[60:61], 18, v3
	s_and_b64 s[62:63], s[64:65], s[62:63]
	v_cmp_gt_i32_e64 s[58:59], 17, v3
	s_and_b64 s[60:61], s[62:63], s[60:61]
	v_cmp_gt_i32_e64 s[56:57], 16, v3
	s_and_b64 s[58:59], s[60:61], s[58:59]
	v_cmp_gt_i32_e64 s[54:55], 11, v3
	s_and_b64 s[56:57], s[58:59], s[56:57]
	v_cmp_gt_i32_e64 s[52:53], 10, v3
	s_and_b64 s[54:55], s[56:57], s[54:55]
	v_cmp_gt_i32_e64 s[50:51], 9, v3
	s_and_b64 s[52:53], s[54:55], s[52:53]
	v_cmp_gt_i32_e64 s[48:49], 8, v3
	s_and_b64 s[50:51], s[52:53], s[50:51]
	v_cmp_gt_i32_e64 s[46:47], 3, v3
	s_and_b64 s[48:49], s[50:51], s[48:49]
	v_cmp_gt_i32_e64 s[44:45], 2, v3
	s_and_b64 s[46:47], s[48:49], s[46:47]
	v_cmp_gt_i32_e64 s[42:43], 1, v3
	s_and_b64 s[44:45], s[46:47], s[44:45]
	v_cmp_gt_i32_e64 s[40:41], 0, v3
	s_and_b64 s[42:43], s[44:45], s[42:43]
	s_and_b64 s[40:41], s[42:43], s[40:41]
	v_cmp_gt_i32_e64 s[36:37], 58, v3
	v_cndmask_b32_e64 v98, v98, v210, s[40:41]
	v_cmp_gt_i32_e64 s[40:41], 59, v3
	v_cmp_gt_i32_e64 s[34:35], 57, v3
	s_and_b64 s[36:37], s[40:41], s[36:37]
	v_cmp_gt_i32_e64 s[30:31], 56, v3
	s_and_b64 s[34:35], s[36:37], s[34:35]
	v_cmp_gt_i32_e64 s[28:29], 51, v3
	s_and_b64 s[30:31], s[34:35], s[30:31]
	v_cmp_gt_i32_e64 s[26:27], 50, v3
	s_and_b64 s[28:29], s[30:31], s[28:29]
	v_cmp_gt_i32_e64 s[24:25], 49, v3
	s_and_b64 s[26:27], s[28:29], s[26:27]
	v_cmp_gt_i32_e64 s[22:23], 48, v3
	s_and_b64 s[24:25], s[26:27], s[24:25]
	v_cmp_gt_i32_e64 s[20:21], 43, v3
	s_and_b64 s[22:23], s[24:25], s[22:23]
	v_cmp_gt_i32_e64 s[18:19], 42, v3
	s_and_b64 s[20:21], s[22:23], s[20:21]
	v_cmp_gt_i32_e64 s[16:17], 41, v3
	s_and_b64 s[18:19], s[20:21], s[18:19]
	v_cmp_gt_i32_e64 s[14:15], 40, v3
	s_and_b64 s[16:17], s[18:19], s[16:17]
	v_cmp_gt_i32_e64 s[12:13], 35, v3
	s_and_b64 s[14:15], s[16:17], s[14:15]
	v_cmp_gt_i32_e64 s[10:11], 34, v3
	s_and_b64 s[12:13], s[14:15], s[12:13]
	v_cmp_gt_i32_e64 s[8:9], 33, v3
	s_and_b64 s[10:11], s[12:13], s[10:11]
	v_cmp_gt_i32_e32 vcc, 32, v3
	s_and_b64 s[8:9], s[10:11], s[8:9]
	s_and_b64 vcc, s[8:9], vcc
	v_cndmask_b32_e64 v113, v113, v210, s[70:71]
	v_cndmask_b32_e64 v112, v112, v210, s[68:69]
	v_cndmask_b32_e64 v111, v111, v210, s[66:67]
	v_cndmask_b32_e64 v110, v110, v210, s[64:65]
	v_cndmask_b32_e64 v109, v109, v210, s[62:63]
	v_cndmask_b32_e64 v108, v108, v210, s[60:61]
	v_cndmask_b32_e64 v107, v107, v210, s[58:59]
	v_cndmask_b32_e64 v106, v106, v210, s[56:57]
	v_cndmask_b32_e64 v105, v105, v210, s[54:55]
	v_cndmask_b32_e64 v104, v104, v210, s[52:53]
	v_cndmask_b32_e64 v103, v103, v210, s[50:51]
	v_cndmask_b32_e64 v102, v102, v210, s[48:49]
	v_cndmask_b32_e64 v101, v101, v210, s[46:47]
	v_cndmask_b32_e64 v100, v100, v210, s[44:45]
	v_cndmask_b32_e64 v99, v99, v210, s[42:43]
	v_cndmask_b32_e64 v97, v97, v210, s[40:41]
	v_cndmask_b32_e64 v96, v96, v210, s[36:37]
	v_cndmask_b32_e64 v95, v95, v210, s[34:35]
	v_cndmask_b32_e64 v94, v94, v210, s[30:31]
	v_cndmask_b32_e64 v93, v93, v210, s[28:29]
	v_cndmask_b32_e64 v92, v92, v210, s[26:27]
	v_cndmask_b32_e64 v91, v91, v210, s[24:25]
	v_cndmask_b32_e64 v90, v90, v210, s[22:23]
	v_cndmask_b32_e64 v89, v89, v210, s[20:21]
	v_cndmask_b32_e64 v88, v88, v210, s[18:19]
	v_cndmask_b32_e64 v87, v87, v210, s[16:17]
	v_cndmask_b32_e64 v86, v86, v210, s[14:15]
	v_cndmask_b32_e64 v85, v85, v210, s[12:13]
	v_cndmask_b32_e64 v84, v84, v210, s[10:11]
	v_cndmask_b32_e64 v83, v83, v210, s[8:9]
	v_cndmask_b32_e32 v82, v82, v210, vcc

.LBB0_624:
	s_and_b32 s16, s14, 0x10000
	s_xor_b32 s17, s16, 0x10000
	v_xor_b32_e32 v217, s16, v215
	v_bitop3_b32 v218, v215, s16, 64 bitop3:0x96
	v_bitop3_b32 v220, v216, s16, 64 bitop3:0x96
	v_xor_b32_e32 v219, s17, v216
	v_xor_b32_e32 v221, s17, v215
	s_waitcnt lgkmcnt(2)
	v_mfma_f32_16x16x32_bf16 v[100:103], v[148:151], v[132:135], v[100:103]
	s_add_i32 s15, s14, 0x10000
	s_and_b32 s17, s15, 0x10000
	s_add_i32 s17, s0, s17
	v_lshl_add_u64 v[246:247], v[174:175], 0, s[12:13]
	s_add_i32 m0, s17, 0x800
	v_mfma_f32_16x16x32_bf16 v[104:107], v[148:151], v[136:139], v[104:107]
	v_mfma_f32_16x16x32_bf16 v[116:119], v[148:151], v[140:143], v[116:119]
	global_load_lds_dwordx4 v[246:247], off
	s_add_i32 m0, s17, 0x8800
	v_lshl_add_u64 v[248:249], v[176:177], 0, s[12:13]
	v_mfma_f32_16x16x32_bf16 v[120:123], v[148:151], v[144:147], v[120:123]
	ds_read_b128 v[148:151], v217 offset:8192
	v_mfma_f32_16x16x32_bf16 v[108:111], v[152:155], v[132:135], v[108:111]
	ds_read_b128 v[222:225], v220
	v_mfma_f32_16x16x32_bf16 v[112:115], v[152:155], v[136:139], v[112:115]
	v_mfma_f32_16x16x32_bf16 v[124:127], v[152:155], v[140:143], v[124:127]
	global_load_lds_dwordx4 v[248:249], off
	s_add_i32 m0, s17, 0xc00
	v_lshl_add_u64 v[246:247], v[172:173], 0, s[12:13]
	v_mfma_f32_16x16x32_bf16 v[128:131], v[152:155], v[144:147], v[128:131]
	ds_read_b128 v[152:155], v217 offset:10240
	s_waitcnt lgkmcnt(3)
	v_mfma_f32_16x16x32_bf16 v[84:87], v[238:241], v[132:135], v[84:87]
	ds_read_b128 v[226:229], v220 offset:2048
	v_mfma_f32_16x16x32_bf16 v[88:91], v[238:241], v[136:139], v[88:91]
	v_mfma_f32_16x16x32_bf16 v[68:71], v[238:241], v[140:143], v[68:71]
	global_load_lds_dwordx4 v[246:247], off
	s_add_i32 m0, s17, 0x8c00
	v_lshl_add_u64 v[248:249], v[170:171], 0, s[12:13]
	v_mfma_f32_16x16x32_bf16 v[72:75], v[238:241], v[144:147], v[72:75]
	ds_read_b128 v[238:241], v217 offset:12288
	v_mfma_f32_16x16x32_bf16 v[92:95], v[242:245], v[132:135], v[92:95]
	ds_read_b128 v[230:233], v220 offset:4096
	v_mfma_f32_16x16x32_bf16 v[96:99], v[242:245], v[136:139], v[96:99]
	v_mfma_f32_16x16x32_bf16 v[76:79], v[242:245], v[140:143], v[76:79]
	global_load_lds_dwordx4 v[248:249], off
	v_mfma_f32_16x16x32_bf16 v[80:83], v[242:245], v[144:147], v[80:83]
	ds_read_b128 v[242:245], v217 offset:14336
	s_waitcnt lgkmcnt(4)
	v_mfma_f32_16x16x32_bf16 v[52:55], v[148:151], v[132:135], v[52:55]
	ds_read_b128 v[234:237], v220 offset:6144
	v_mfma_f32_16x16x32_bf16 v[56:59], v[148:151], v[136:139], v[56:59]
	v_mfma_f32_16x16x32_bf16 v[36:39], v[148:151], v[140:143], v[36:39]
	v_mfma_f32_16x16x32_bf16 v[40:43], v[148:151], v[144:147], v[40:43]
	ds_read_b128 v[148:151], v218
	v_mfma_f32_16x16x32_bf16 v[60:63], v[152:155], v[132:135], v[60:63]
	v_mfma_f32_16x16x32_bf16 v[64:67], v[152:155], v[136:139], v[64:67]
	v_mfma_f32_16x16x32_bf16 v[44:47], v[152:155], v[140:143], v[44:47]
	v_mfma_f32_16x16x32_bf16 v[48:51], v[152:155], v[144:147], v[48:51]
	ds_read_b128 v[152:155], v218 offset:2048
	s_waitcnt lgkmcnt(3)
	v_mfma_f32_16x16x32_bf16 v[20:23], v[238:241], v[132:135], v[20:23]
	v_mfma_f32_16x16x32_bf16 v[24:27], v[238:241], v[136:139], v[24:27]
	v_mfma_f32_16x16x32_bf16 v[4:7], v[238:241], v[140:143], v[4:7]
	v_mfma_f32_16x16x32_bf16 v[8:11], v[238:241], v[144:147], v[8:11]
	ds_read_b128 v[238:241], v218 offset:4096
	v_mfma_f32_16x16x32_bf16 v[28:31], v[242:245], v[132:135], v[28:31]
	v_mfma_f32_16x16x32_bf16 v[32:35], v[242:245], v[136:139], v[32:35]
	v_mfma_f32_16x16x32_bf16 v[12:15], v[242:245], v[140:143], v[12:15]
	v_mfma_f32_16x16x32_bf16 v[16:19], v[242:245], v[144:147], v[16:19]
	ds_read_b128 v[242:245], v218 offset:6144
	s_waitcnt lgkmcnt(2)
	v_mfma_f32_16x16x32_bf16 v[100:103], v[148:151], v[222:225], v[100:103]
	v_mfma_f32_16x16x32_bf16 v[104:107], v[148:151], v[226:229], v[104:107]
	v_mfma_f32_16x16x32_bf16 v[116:119], v[148:151], v[230:233], v[116:119]
	v_mfma_f32_16x16x32_bf16 v[120:123], v[148:151], v[234:237], v[120:123]
	ds_read_b128 v[148:151], v218 offset:8192
	v_mfma_f32_16x16x32_bf16 v[108:111], v[152:155], v[222:225], v[108:111]
	v_mfma_f32_16x16x32_bf16 v[112:115], v[152:155], v[226:229], v[112:115]
	v_mfma_f32_16x16x32_bf16 v[124:127], v[152:155], v[230:233], v[124:127]
	v_mfma_f32_16x16x32_bf16 v[128:131], v[152:155], v[234:237], v[128:131]
	ds_read_b128 v[152:155], v218 offset:10240
	s_waitcnt lgkmcnt(2)
	v_mfma_f32_16x16x32_bf16 v[84:87], v[238:241], v[222:225], v[84:87]
	v_mfma_f32_16x16x32_bf16 v[88:91], v[238:241], v[226:229], v[88:91]
	v_mfma_f32_16x16x32_bf16 v[68:71], v[238:241], v[230:233], v[68:71]
	v_mfma_f32_16x16x32_bf16 v[72:75], v[238:241], v[234:237], v[72:75]
	ds_read_b128 v[238:241], v218 offset:12288
	v_mfma_f32_16x16x32_bf16 v[92:95], v[242:245], v[222:225], v[92:95]
	v_mfma_f32_16x16x32_bf16 v[96:99], v[242:245], v[226:229], v[96:99]
	v_mfma_f32_16x16x32_bf16 v[76:79], v[242:245], v[230:233], v[76:79]
	v_mfma_f32_16x16x32_bf16 v[80:83], v[242:245], v[234:237], v[80:83]
	ds_read_b128 v[242:245], v218 offset:14336
	s_waitcnt lgkmcnt(2)
	v_mfma_f32_16x16x32_bf16 v[52:55], v[148:151], v[222:225], v[52:55]
	v_mfma_f32_16x16x32_bf16 v[56:59], v[148:151], v[226:229], v[56:59]
	v_mfma_f32_16x16x32_bf16 v[36:39], v[148:151], v[230:233], v[36:39]
	v_mfma_f32_16x16x32_bf16 v[40:43], v[148:151], v[234:237], v[40:43]
	s_add_i32 s3, s3, 1
	s_min_i32 s38, s3, s1
	s_ashr_i32 s39, s38, 31
	s_lshl_b64 s[38:39], s[38:39], 7
	s_add_i32 s14, s0, s16
	v_lshl_add_u64 v[246:247], v[162:163], 0, s[38:39]
	s_mov_b32 m0, s14
	s_waitcnt vmcnt(0) lgkmcnt(0)
	s_barrier
	ds_read_b128 v[132:135], v219
	ds_read_b128 v[136:139], v219 offset:2048
	v_mfma_f32_16x16x32_bf16 v[60:63], v[152:155], v[222:225], v[60:63]
	ds_read_b128 v[140:143], v219 offset:4096
	ds_read_b128 v[144:147], v219 offset:6144
	v_mfma_f32_16x16x32_bf16 v[64:67], v[152:155], v[226:229], v[64:67]
	global_load_lds_dwordx4 v[246:247], off
	s_add_i32 m0, s14, 0x8000
	s_add_u32 s16, s38, s10
	v_lshl_add_u64 v[248:249], v[164:165], 0, s[38:39]
	s_addc_u32 s17, s39, s11
	ds_read_b128 v[148:151], v221
	v_mfma_f32_16x16x32_bf16 v[44:47], v[152:155], v[230:233], v[44:47]
	v_mfma_f32_16x16x32_bf16 v[48:51], v[152:155], v[234:237], v[48:51]
	global_load_lds_dwordx4 v[248:249], off
	s_add_i32 m0, s14, 0x400
	v_lshl_add_u64 v[246:247], v[166:167], 0, s[16:17]
	ds_read_b128 v[152:155], v221 offset:2048
	v_mfma_f32_16x16x32_bf16 v[20:23], v[238:241], v[222:225], v[20:23]
	v_mfma_f32_16x16x32_bf16 v[24:27], v[238:241], v[226:229], v[24:27]
	global_load_lds_dwordx4 v[246:247], off
	s_add_i32 m0, s14, 0x8400
	v_lshl_add_u64 v[248:249], v[168:169], 0, s[16:17]
	v_mfma_f32_16x16x32_bf16 v[4:7], v[238:241], v[230:233], v[4:7]
	v_mfma_f32_16x16x32_bf16 v[8:11], v[238:241], v[234:237], v[8:11]
	global_load_lds_dwordx4 v[248:249], off
	ds_read_b128 v[238:241], v221 offset:4096
	v_mfma_f32_16x16x32_bf16 v[28:31], v[242:245], v[222:225], v[28:31]
	v_mfma_f32_16x16x32_bf16 v[32:35], v[242:245], v[226:229], v[32:35]
	v_mfma_f32_16x16x32_bf16 v[12:15], v[242:245], v[230:233], v[12:15]
	v_mfma_f32_16x16x32_bf16 v[16:19], v[242:245], v[234:237], v[16:19]
	ds_read_b128 v[242:245], v221 offset:6144
	s_add_u32 s12, s12, 0x80
	s_addc_u32 s13, s13, 0
	s_cmp_eq_u32 s5, s3
	s_mov_b32 s14, s15
	s_cbranch_scc0 .LBB0_624
	s_branch .LBB0_626

.LBB0_626:
	s_not_b32 s0, s5
	s_lshl_b32 s0, s0, 16
	s_and_b32 s0, s0, 0x10000
	v_xor_b32_e32 v217, s0, v215
	v_bitop3_b32 v218, v215, s0, 64 bitop3:0x96
	v_bitop3_b32 v220, v216, s0, 64 bitop3:0x96
	s_waitcnt lgkmcnt(2)
	v_mfma_f32_16x16x32_bf16 v[100:103], v[148:151], v[132:135], v[100:103]
	v_mfma_f32_16x16x32_bf16 v[104:107], v[148:151], v[136:139], v[104:107]
	v_mfma_f32_16x16x32_bf16 v[116:119], v[148:151], v[140:143], v[116:119]
	v_mfma_f32_16x16x32_bf16 v[120:123], v[148:151], v[144:147], v[120:123]
	ds_read_b128 v[148:151], v217 offset:8192
	v_mfma_f32_16x16x32_bf16 v[108:111], v[152:155], v[132:135], v[108:111]
	ds_read_b128 v[222:225], v220
	v_mfma_f32_16x16x32_bf16 v[112:115], v[152:155], v[136:139], v[112:115]
	v_mfma_f32_16x16x32_bf16 v[124:127], v[152:155], v[140:143], v[124:127]
	v_mfma_f32_16x16x32_bf16 v[128:131], v[152:155], v[144:147], v[128:131]
	ds_read_b128 v[152:155], v217 offset:10240
	s_waitcnt lgkmcnt(3)
	v_mfma_f32_16x16x32_bf16 v[84:87], v[238:241], v[132:135], v[84:87]
	ds_read_b128 v[226:229], v220 offset:2048
	v_mfma_f32_16x16x32_bf16 v[88:91], v[238:241], v[136:139], v[88:91]
	v_mfma_f32_16x16x32_bf16 v[68:71], v[238:241], v[140:143], v[68:71]
	v_mfma_f32_16x16x32_bf16 v[72:75], v[238:241], v[144:147], v[72:75]
	ds_read_b128 v[238:241], v217 offset:12288
	v_mfma_f32_16x16x32_bf16 v[92:95], v[242:245], v[132:135], v[92:95]
	ds_read_b128 v[230:233], v220 offset:4096
	v_mfma_f32_16x16x32_bf16 v[96:99], v[242:245], v[136:139], v[96:99]
	v_mfma_f32_16x16x32_bf16 v[76:79], v[242:245], v[140:143], v[76:79]
	v_mfma_f32_16x16x32_bf16 v[80:83], v[242:245], v[144:147], v[80:83]
	ds_read_b128 v[242:245], v217 offset:14336
	s_waitcnt lgkmcnt(4)
	v_mfma_f32_16x16x32_bf16 v[52:55], v[148:151], v[132:135], v[52:55]
	ds_read_b128 v[234:237], v220 offset:6144
	v_mfma_f32_16x16x32_bf16 v[56:59], v[148:151], v[136:139], v[56:59]
	v_mfma_f32_16x16x32_bf16 v[36:39], v[148:151], v[140:143], v[36:39]
	v_mfma_f32_16x16x32_bf16 v[40:43], v[148:151], v[144:147], v[40:43]
	ds_read_b128 v[148:151], v218
	v_mfma_f32_16x16x32_bf16 v[60:63], v[152:155], v[132:135], v[60:63]
	v_mfma_f32_16x16x32_bf16 v[64:67], v[152:155], v[136:139], v[64:67]
	v_mfma_f32_16x16x32_bf16 v[44:47], v[152:155], v[140:143], v[44:47]
	v_mfma_f32_16x16x32_bf16 v[48:51], v[152:155], v[144:147], v[48:51]
	ds_read_b128 v[152:155], v218 offset:2048
	s_waitcnt lgkmcnt(3)
	v_mfma_f32_16x16x32_bf16 v[20:23], v[238:241], v[132:135], v[20:23]
	v_mfma_f32_16x16x32_bf16 v[24:27], v[238:241], v[136:139], v[24:27]
	v_mfma_f32_16x16x32_bf16 v[4:7], v[238:241], v[140:143], v[4:7]
	v_mfma_f32_16x16x32_bf16 v[8:11], v[238:241], v[144:147], v[8:11]
	ds_read_b128 v[238:241], v218 offset:4096
	v_mfma_f32_16x16x32_bf16 v[28:31], v[242:245], v[132:135], v[28:31]
	v_mfma_f32_16x16x32_bf16 v[32:35], v[242:245], v[136:139], v[32:35]
	v_mfma_f32_16x16x32_bf16 v[12:15], v[242:245], v[140:143], v[12:15]
	v_mfma_f32_16x16x32_bf16 v[16:19], v[242:245], v[144:147], v[16:19]
	ds_read_b128 v[242:245], v218 offset:6144
	s_waitcnt lgkmcnt(2)
	v_mfma_f32_16x16x32_bf16 v[100:103], v[148:151], v[222:225], v[100:103]
	v_mfma_f32_16x16x32_bf16 v[104:107], v[148:151], v[226:229], v[104:107]
	v_mfma_f32_16x16x32_bf16 v[116:119], v[148:151], v[230:233], v[116:119]
	v_mfma_f32_16x16x32_bf16 v[120:123], v[148:151], v[234:237], v[120:123]
	ds_read_b128 v[148:151], v218 offset:8192
	v_mfma_f32_16x16x32_bf16 v[108:111], v[152:155], v[222:225], v[108:111]
	v_mfma_f32_16x16x32_bf16 v[112:115], v[152:155], v[226:229], v[112:115]
	v_mfma_f32_16x16x32_bf16 v[124:127], v[152:155], v[230:233], v[124:127]
	v_mfma_f32_16x16x32_bf16 v[128:131], v[152:155], v[234:237], v[128:131]
	ds_read_b128 v[152:155], v218 offset:10240
	s_waitcnt lgkmcnt(2)
	v_mfma_f32_16x16x32_bf16 v[84:87], v[238:241], v[222:225], v[84:87]
	v_mfma_f32_16x16x32_bf16 v[88:91], v[238:241], v[226:229], v[88:91]
	v_mfma_f32_16x16x32_bf16 v[68:71], v[238:241], v[230:233], v[68:71]
	v_mfma_f32_16x16x32_bf16 v[72:75], v[238:241], v[234:237], v[72:75]
	ds_read_b128 v[238:241], v218 offset:12288
	v_mfma_f32_16x16x32_bf16 v[92:95], v[242:245], v[222:225], v[92:95]
	v_mfma_f32_16x16x32_bf16 v[96:99], v[242:245], v[226:229], v[96:99]
	v_mfma_f32_16x16x32_bf16 v[76:79], v[242:245], v[230:233], v[76:79]
	v_mfma_f32_16x16x32_bf16 v[80:83], v[242:245], v[234:237], v[80:83]
	ds_read_b128 v[242:245], v218 offset:14336
	s_waitcnt lgkmcnt(2)
	v_mfma_f32_16x16x32_bf16 v[52:55], v[148:151], v[222:225], v[52:55]
	v_mfma_f32_16x16x32_bf16 v[56:59], v[148:151], v[226:229], v[56:59]
	v_mfma_f32_16x16x32_bf16 v[36:39], v[148:151], v[230:233], v[36:39]
	v_mfma_f32_16x16x32_bf16 v[40:43], v[148:151], v[234:237], v[40:43]
	s_waitcnt vmcnt(0) lgkmcnt(0)
	s_barrier
	v_mfma_f32_16x16x32_bf16 v[60:63], v[152:155], v[222:225], v[60:63]
	v_mfma_f32_16x16x32_bf16 v[64:67], v[152:155], v[226:229], v[64:67]
	v_mfma_f32_16x16x32_bf16 v[44:47], v[152:155], v[230:233], v[44:47]
	v_mfma_f32_16x16x32_bf16 v[48:51], v[152:155], v[234:237], v[48:51]
	v_mfma_f32_16x16x32_bf16 v[20:23], v[238:241], v[222:225], v[20:23]
	v_mfma_f32_16x16x32_bf16 v[24:27], v[238:241], v[226:229], v[24:27]
	v_mfma_f32_16x16x32_bf16 v[4:7], v[238:241], v[230:233], v[4:7]
	v_mfma_f32_16x16x32_bf16 v[8:11], v[238:241], v[234:237], v[8:11]
	v_mfma_f32_16x16x32_bf16 v[28:31], v[242:245], v[222:225], v[28:31]
	v_mfma_f32_16x16x32_bf16 v[32:35], v[242:245], v[226:229], v[32:35]
	v_mfma_f32_16x16x32_bf16 v[12:15], v[242:245], v[230:233], v[12:15]
	v_mfma_f32_16x16x32_bf16 v[16:19], v[242:245], v[234:237], v[16:19]
	s_nop 7
	s_nop 7
	v_permlane16_swap_b32_e32 v100, v104
	v_permlane16_swap_b32_e32 v101, v105
	v_permlane16_swap_b32_e32 v102, v106
	v_permlane16_swap_b32_e32 v103, v107
	v_permlane16_swap_b32_e32 v108, v112
	v_permlane16_swap_b32_e32 v109, v113
	v_permlane16_swap_b32_e32 v110, v114
	v_permlane16_swap_b32_e32 v111, v115
	v_permlane16_swap_b32_e32 v116, v120
	v_permlane16_swap_b32_e32 v117, v121
	v_permlane16_swap_b32_e32 v118, v122
	v_permlane16_swap_b32_e32 v119, v123
	v_permlane16_swap_b32_e32 v124, v128
	v_permlane16_swap_b32_e32 v125, v129
	v_permlane16_swap_b32_e32 v126, v130
	v_permlane16_swap_b32_e32 v127, v131
	v_permlane16_swap_b32_e32 v84, v88
	v_permlane16_swap_b32_e32 v85, v89
	v_permlane16_swap_b32_e32 v86, v90
	v_permlane16_swap_b32_e32 v87, v91
	v_permlane16_swap_b32_e32 v92, v96
	v_permlane16_swap_b32_e32 v93, v97
	v_permlane16_swap_b32_e32 v94, v98
	v_permlane16_swap_b32_e32 v95, v99
	v_permlane16_swap_b32_e32 v68, v72
	v_permlane16_swap_b32_e32 v69, v73
	v_permlane16_swap_b32_e32 v70, v74
	v_permlane16_swap_b32_e32 v71, v75
	v_permlane16_swap_b32_e32 v76, v80
	v_permlane16_swap_b32_e32 v77, v81
	v_permlane16_swap_b32_e32 v78, v82
	v_permlane16_swap_b32_e32 v79, v83
	v_permlane16_swap_b32_e32 v52, v56
	v_permlane16_swap_b32_e32 v53, v57
	v_permlane16_swap_b32_e32 v54, v58
	v_permlane16_swap_b32_e32 v55, v59
	v_permlane16_swap_b32_e32 v60, v64
	v_permlane16_swap_b32_e32 v61, v65
	v_permlane16_swap_b32_e32 v62, v66
	v_permlane16_swap_b32_e32 v63, v67
	v_permlane16_swap_b32_e32 v36, v40
	v_permlane16_swap_b32_e32 v37, v41
	v_permlane16_swap_b32_e32 v38, v42
	v_permlane16_swap_b32_e32 v39, v43
	v_permlane16_swap_b32_e32 v44, v48
	v_permlane16_swap_b32_e32 v45, v49
	v_permlane16_swap_b32_e32 v46, v50
	v_permlane16_swap_b32_e32 v47, v51
	v_permlane16_swap_b32_e32 v20, v24
	v_permlane16_swap_b32_e32 v21, v25
	v_permlane16_swap_b32_e32 v22, v26
	v_permlane16_swap_b32_e32 v23, v27
	v_permlane16_swap_b32_e32 v28, v32
	v_permlane16_swap_b32_e32 v29, v33
	v_permlane16_swap_b32_e32 v30, v34
	v_permlane16_swap_b32_e32 v31, v35
	v_permlane16_swap_b32_e32 v4, v8
	v_permlane16_swap_b32_e32 v5, v9
	v_permlane16_swap_b32_e32 v6, v10
	v_permlane16_swap_b32_e32 v7, v11
	v_permlane16_swap_b32_e32 v12, v16
	v_permlane16_swap_b32_e32 v13, v17
	v_permlane16_swap_b32_e32 v14, v18
	v_permlane16_swap_b32_e32 v15, v19
	s_and_b64 vcc, exec, s[8:9]
	s_cbranch_vccz .LBB0_628
	v_lshlrev_b32_e32 v132, 4, v213
	v_lshl_add_u32 v132, s18, 2, v132
	v_add_u32_e32 v148, 0x20000, v132
	ds_read_b128 v[132:135], v148
	ds_read_b128 v[136:139], v148 offset:32
	ds_read_b128 v[140:143], v148 offset:64
	ds_read_b128 v[144:147], v148 offset:96
	s_waitcnt lgkmcnt(3)
	v_pk_mul_f32 v[102:103], v[102:103], v[134:135]
	s_waitcnt lgkmcnt(2)
	v_pk_mul_f32 v[104:105], v[104:105], v[136:137]
	s_waitcnt lgkmcnt(1)
	v_pk_mul_f32 v[108:109], v[108:109], v[140:141]
	s_waitcnt lgkmcnt(0)
	v_pk_mul_f32 v[112:113], v[112:113], v[144:145]
	v_pk_mul_f32 v[114:115], v[114:115], v[146:147]
	v_pk_mul_f32 v[110:111], v[110:111], v[142:143]
	v_pk_mul_f32 v[106:107], v[106:107], v[138:139]
	v_pk_mul_f32 v[100:101], v[100:101], v[132:133]
	v_pk_mul_f32 v[128:129], v[128:129], v[144:145]
	v_pk_mul_f32 v[124:125], v[124:125], v[140:141]
	v_pk_mul_f32 v[120:121], v[120:121], v[136:137]
	v_pk_mul_f32 v[130:131], v[130:131], v[146:147]
	v_pk_mul_f32 v[126:127], v[126:127], v[142:143]
	v_pk_mul_f32 v[122:123], v[122:123], v[138:139]
	v_pk_mul_f32 v[118:119], v[118:119], v[134:135]
	v_pk_mul_f32 v[116:117], v[116:117], v[132:133]
	ds_read_b128 v[132:135], v148 offset:128
	ds_read_b128 v[136:139], v148 offset:160
	ds_read_b128 v[140:143], v148 offset:192
	ds_read_b128 v[144:147], v148 offset:224
	s_waitcnt lgkmcnt(3)
	v_pk_mul_f32 v[86:87], v[86:87], v[134:135]
	s_waitcnt lgkmcnt(2)
	v_pk_mul_f32 v[88:89], v[88:89], v[136:137]
	s_waitcnt lgkmcnt(1)
	v_pk_mul_f32 v[92:93], v[92:93], v[140:141]
	s_waitcnt lgkmcnt(0)
	v_pk_mul_f32 v[96:97], v[96:97], v[144:145]
	v_pk_mul_f32 v[98:99], v[98:99], v[146:147]
	v_pk_mul_f32 v[94:95], v[94:95], v[142:143]
	v_pk_mul_f32 v[90:91], v[90:91], v[138:139]
	v_pk_mul_f32 v[84:85], v[84:85], v[132:133]
	v_pk_mul_f32 v[80:81], v[80:81], v[144:145]
	v_pk_mul_f32 v[76:77], v[76:77], v[140:141]
	v_pk_mul_f32 v[72:73], v[72:73], v[136:137]
	v_pk_mul_f32 v[82:83], v[82:83], v[146:147]
	v_pk_mul_f32 v[78:79], v[78:79], v[142:143]
	v_pk_mul_f32 v[74:75], v[74:75], v[138:139]
	v_pk_mul_f32 v[70:71], v[70:71], v[134:135]
	v_pk_mul_f32 v[68:69], v[68:69], v[132:133]
	ds_read_b128 v[132:135], v148 offset:256
	ds_read_b128 v[136:139], v148 offset:288
	ds_read_b128 v[140:143], v148 offset:320
	ds_read_b128 v[144:147], v148 offset:352
	s_waitcnt lgkmcnt(3)
	v_pk_mul_f32 v[54:55], v[54:55], v[134:135]
	s_waitcnt lgkmcnt(2)
	v_pk_mul_f32 v[56:57], v[56:57], v[136:137]
	s_waitcnt lgkmcnt(1)
	v_pk_mul_f32 v[60:61], v[60:61], v[140:141]
	s_waitcnt lgkmcnt(0)
	v_pk_mul_f32 v[64:65], v[64:65], v[144:145]
	v_pk_mul_f32 v[66:67], v[66:67], v[146:147]
	v_pk_mul_f32 v[62:63], v[62:63], v[142:143]
	v_pk_mul_f32 v[58:59], v[58:59], v[138:139]
	v_pk_mul_f32 v[52:53], v[52:53], v[132:133]
	v_pk_mul_f32 v[48:49], v[48:49], v[144:145]
	v_pk_mul_f32 v[44:45], v[44:45], v[140:141]
	v_pk_mul_f32 v[40:41], v[40:41], v[136:137]
	v_pk_mul_f32 v[50:51], v[50:51], v[146:147]
	v_pk_mul_f32 v[46:47], v[46:47], v[142:143]
	v_pk_mul_f32 v[42:43], v[42:43], v[138:139]
	v_pk_mul_f32 v[38:39], v[38:39], v[134:135]
	v_pk_mul_f32 v[36:37], v[36:37], v[132:133]
	ds_read_b128 v[132:135], v148 offset:384
	ds_read_b128 v[136:139], v148 offset:416
	ds_read_b128 v[140:143], v148 offset:448
	ds_read_b128 v[144:147], v148 offset:480
	s_waitcnt lgkmcnt(3)
	v_pk_mul_f32 v[22:23], v[22:23], v[134:135]
	s_waitcnt lgkmcnt(2)
	v_pk_mul_f32 v[24:25], v[24:25], v[136:137]
	s_waitcnt lgkmcnt(1)
	v_pk_mul_f32 v[28:29], v[28:29], v[140:141]
	s_waitcnt lgkmcnt(0)
	v_pk_mul_f32 v[32:33], v[32:33], v[144:145]
	v_pk_mul_f32 v[34:35], v[34:35], v[146:147]
	v_pk_mul_f32 v[30:31], v[30:31], v[142:143]
	v_pk_mul_f32 v[26:27], v[26:27], v[138:139]
	v_pk_mul_f32 v[20:21], v[20:21], v[132:133]
	v_pk_mul_f32 v[16:17], v[16:17], v[144:145]
	v_pk_mul_f32 v[12:13], v[12:13], v[140:141]
	v_pk_mul_f32 v[8:9], v[8:9], v[136:137]
	v_pk_mul_f32 v[18:19], v[18:19], v[146:147]
	v_pk_mul_f32 v[14:15], v[14:15], v[142:143]
	v_pk_mul_f32 v[10:11], v[10:11], v[138:139]
	v_pk_mul_f32 v[6:7], v[6:7], v[134:135]
	v_pk_mul_f32 v[4:5], v[4:5], v[132:133]
